# scan loop: next-chunk loads unconditional + issued before the v_new stores, vmcnt recounted (loads no longer retire behind store acks)
# speedup vs baseline: 1.0103x; 1.0062x over previous
.LBB0_1201:
	global_load_dword v168, v169, s[6:7]
	s_cmpk_lt_u32 s16, 0x7e
	s_cselect_b64 s[12:13], -1, 0
	s_cmpk_gt_u32 s16, 0x7d
	s_cselect_b64 s[10:11], -1, 0
	s_and_b64 vcc, exec, s[10:11]
	s_add_i32 s4, s0, s16
	s_add_i32 s4, s4, 2
	s_ashr_i32 s5, s4, 31
	s_lshl_b64 s[4:5], s[4:5], 14
	s_add_u32 s18, s2, s4
	s_addc_u32 s19, s3, s5
	s_add_u32 s4, s14, s4
	s_addc_u32 s5, s15, s5
	v_lshl_add_u64 v[64:65], s[18:19], 0, v[160:161]
	v_lshl_add_u64 v[66:67], s[4:5], 0, v[160:161]
	global_load_dwordx4 v[96:99], v[64:65], off
	global_load_dwordx4 v[100:103], v[66:67], off
	v_lshl_add_u64 v[64:65], s[18:19], 0, v[162:163]
	v_lshl_add_u64 v[66:67], s[4:5], 0, v[162:163]
	global_load_dwordx4 v[104:107], v[64:65], off
	global_load_dwordx4 v[108:111], v[66:67], off
	v_lshl_add_u64 v[64:65], s[18:19], 0, v[164:165]
	v_lshl_add_u64 v[66:67], s[4:5], 0, v[164:165]
	global_load_dwordx4 v[112:115], v[64:65], off
	global_load_dwordx4 v[116:119], v[66:67], off
	v_lshl_add_u64 v[64:65], s[18:19], 0, v[166:167]
	v_lshl_add_u64 v[66:67], s[4:5], 0, v[166:167]
	global_load_dwordx4 v[120:123], v[64:65], off
	global_load_dwordx4 v[124:127], v[66:67], off
.LBB0_1203:
	v_add_u32_e32 v208, 0x2000, v206
	ds_read2_b64 v[64:67], v206 offset1:2
	ds_read2_b64 v[210:213], v206 offset0:4 offset1:6
	ds_read2_b64 v[68:71], v208 offset0:32 offset1:34
	ds_read2_b64 v[214:217], v208 offset0:36 offset1:38
	v_ashrrev_i32_e32 v185, 31, v184
	v_lshlrev_b64 v[226:227], 13, v[184:185]
	v_cvt_pk_bf16_f32 v218, v0, v1
	v_cvt_pk_bf16_f32 v219, v2, v3
	v_cvt_pk_bf16_f32 v220, v4, v5
	v_cvt_pk_bf16_f32 v221, v6, v7
	v_lshl_add_u64 v[234:235], v[178:179], 0, v[226:227]
	v_cvt_pk_bf16_f32 v222, v8, v9
	s_waitcnt lgkmcnt(3)
	v_mfma_f32_32x32x16_bf16 v[80:95], v[64:67], v[218:221], 0
	v_cvt_pk_bf16_f32 v223, v10, v11
	v_cvt_pk_bf16_f32 v224, v12, v13
	v_cvt_pk_bf16_f32 v225, v14, v15
	global_store_dwordx4 v[234:235], v[218:221], off
	global_store_dwordx4 v[234:235], v[222:225], off offset:1024
	s_waitcnt lgkmcnt(1)
	v_mfma_f32_32x32x16_bf16 v[64:79], v[68:71], v[218:221], 0
	v_mfma_f32_32x32x16_bf16 v[80:95], v[210:213], v[222:225], v[80:95]
	ds_read2_b64 v[210:213], v206 offset0:8 offset1:10
	ds_read2_b64 v[218:221], v206 offset0:12 offset1:14
	ds_read2_b64 v[226:229], v208 offset0:40 offset1:42
	ds_read2_b64 v[230:233], v208 offset0:44 offset1:46
	s_waitcnt lgkmcnt(4)
	v_mfma_f32_32x32x16_bf16 v[64:79], v[214:217], v[222:225], v[64:79]
	v_cvt_pk_bf16_f32 v214, v16, v17
	v_cvt_pk_bf16_f32 v215, v18, v19
	v_cvt_pk_bf16_f32 v216, v20, v21
	v_cvt_pk_bf16_f32 v217, v22, v23
	s_waitcnt lgkmcnt(3)
	s_nop 0
	v_mfma_f32_32x32x16_bf16 v[80:95], v[210:213], v[214:217], v[80:95]
	v_cvt_pk_bf16_f32 v210, v24, v25
	v_cvt_pk_bf16_f32 v211, v26, v27
	v_cvt_pk_bf16_f32 v212, v28, v29
	v_cvt_pk_bf16_f32 v213, v30, v31
	global_store_dwordx4 v[234:235], v[214:217], off offset:2048
	global_store_dwordx4 v[234:235], v[210:213], off offset:3072
	s_waitcnt lgkmcnt(1)
	v_mfma_f32_32x32x16_bf16 v[64:79], v[226:229], v[214:217], v[64:79]
	v_mfma_f32_32x32x16_bf16 v[80:95], v[218:221], v[210:213], v[80:95]
	ds_read2_b64 v[214:217], v206 offset0:16 offset1:18
	ds_read2_b64 v[218:221], v206 offset0:20 offset1:22
	ds_read2_b64 v[222:225], v208 offset0:48 offset1:50
	ds_read2_b64 v[226:229], v208 offset0:52 offset1:54
	s_waitcnt lgkmcnt(4)
	v_mfma_f32_32x32x16_bf16 v[64:79], v[230:233], v[210:213], v[64:79]
	v_cvt_pk_bf16_f32 v210, v32, v33
	v_cvt_pk_bf16_f32 v211, v34, v35
	v_cvt_pk_bf16_f32 v212, v36, v37
	v_cvt_pk_bf16_f32 v213, v38, v39
	v_add_co_u32_e32 v234, vcc, s1, v234
	s_waitcnt lgkmcnt(3)
	v_mfma_f32_32x32x16_bf16 v[80:95], v[214:217], v[210:213], v[80:95]
	v_addc_co_u32_e32 v235, vcc, 0, v235, vcc
	v_cvt_pk_bf16_f32 v214, v40, v41
	v_cvt_pk_bf16_f32 v215, v42, v43
	v_cvt_pk_bf16_f32 v216, v44, v45
	v_cvt_pk_bf16_f32 v217, v46, v47
	global_store_dwordx4 v[234:235], v[210:213], off
	global_store_dwordx4 v[234:235], v[214:217], off offset:1024
	s_waitcnt lgkmcnt(1)
	v_mfma_f32_32x32x16_bf16 v[64:79], v[222:225], v[210:213], v[64:79]
	v_mfma_f32_32x32x16_bf16 v[80:95], v[218:221], v[214:217], v[80:95]
	ds_read2_b64 v[210:213], v206 offset0:24 offset1:26
	ds_read2_b64 v[218:221], v206 offset0:28 offset1:30
	ds_read2_b64 v[222:225], v208 offset0:56 offset1:58
	ds_read2_b64 v[230:233], v208 offset0:60 offset1:62
	s_waitcnt lgkmcnt(4)
	v_mfma_f32_32x32x16_bf16 v[64:79], v[226:229], v[214:217], v[64:79]
	v_cvt_pk_bf16_f32 v214, v48, v49
	v_cvt_pk_bf16_f32 v215, v50, v51
	v_cvt_pk_bf16_f32 v216, v52, v53
	v_cvt_pk_bf16_f32 v217, v54, v55
	v_cvt_pk_bf16_f32 v226, v56, v57
	v_cvt_pk_bf16_f32 v227, v58, v59
	s_waitcnt lgkmcnt(3)
	v_mfma_f32_32x32x16_bf16 v[80:95], v[210:213], v[214:217], v[80:95]
	v_cvt_pk_bf16_f32 v228, v60, v61
	v_cvt_pk_bf16_f32 v229, v62, v63
	s_waitcnt vmcnt(26)
	v_lshlrev_b32_e32 v212, 16, v196
	v_and_b32_e32 v213, 0xffff0000, v196
	v_lshlrev_b32_e32 v196, 16, v197
	v_and_b32_e32 v197, 0xffff0000, v197
	v_lshlrev_b64 v[210:211], 12, v[184:185]
	s_waitcnt lgkmcnt(1)
	v_mfma_f32_32x32x16_bf16 v[64:79], v[222:225], v[214:217], v[64:79]
	v_lshl_add_u64 v[210:211], v[180:181], 0, v[210:211]
	global_store_dwordx4 v[234:235], v[214:217], off offset:2048
	global_store_dwordx4 v[234:235], v[226:229], off offset:3072
	v_mfma_f32_32x32x16_bf16 v[80:95], v[218:221], v[226:229], v[80:95]
	s_waitcnt lgkmcnt(0)
	v_mfma_f32_32x32x16_bf16 v[64:79], v[230:233], v[226:229], v[64:79]
	s_nop 9
	v_add_f32_e64 v82, v196, -v82
	v_add_f32_e64 v83, v197, -v83
	s_waitcnt vmcnt(27)
	v_lshlrev_b32_e32 v196, 16, v194
	v_and_b32_e32 v197, 0xffff0000, v194
	v_pk_add_f32 v[196:197], v[196:197], v[84:85] neg_lo:[0,1] neg_hi:[0,1]
	v_lshlrev_b32_e32 v84, 16, v195
	v_and_b32_e32 v85, 0xffff0000, v195
	v_pk_add_f32 v[194:195], v[84:85], v[86:87] neg_lo:[0,1] neg_hi:[0,1]
	s_waitcnt vmcnt(26)
	v_lshlrev_b32_e32 v84, 16, v192
	v_and_b32_e32 v85, 0xffff0000, v192
	v_pk_add_f32 v[88:89], v[84:85], v[88:89] neg_lo:[0,1] neg_hi:[0,1]
	v_lshlrev_b32_e32 v84, 16, v193
	v_and_b32_e32 v85, 0xffff0000, v193
	v_pk_add_f32 v[90:91], v[84:85], v[90:91] neg_lo:[0,1] neg_hi:[0,1]
	s_waitcnt vmcnt(25)
	v_lshlrev_b32_e32 v84, 16, v190
	v_and_b32_e32 v85, 0xffff0000, v190
	v_pk_add_f32 v[80:81], v[212:213], v[80:81] neg_lo:[0,1] neg_hi:[0,1]
	v_pk_add_f32 v[92:93], v[84:85], v[92:93] neg_lo:[0,1] neg_hi:[0,1]
	v_lshlrev_b32_e32 v84, 16, v191
	v_sub_f32_e32 v94, v84, v94
	v_cvt_pk_bf16_f32 v84, v80, v81
	v_cvt_pk_bf16_f32 v80, v88, v89
	s_waitcnt vmcnt(24)
	v_lshlrev_b32_e32 v88, 16, v186
	v_and_b32_e32 v89, 0xffff0000, v186
	v_pk_add_f32 v[64:65], v[88:89], v[64:65] neg_lo:[0,1] neg_hi:[0,1]
	v_lshlrev_b32_e32 v88, 16, v187
	v_and_b32_e32 v89, 0xffff0000, v187
	v_pk_add_f32 v[66:67], v[88:89], v[66:67] neg_lo:[0,1] neg_hi:[0,1]
	s_waitcnt vmcnt(23)
	v_lshlrev_b32_e32 v88, 16, v176
	v_and_b32_e32 v89, 0xffff0000, v176
	v_pk_add_f32 v[88:89], v[88:89], v[68:69] neg_lo:[0,1] neg_hi:[0,1]
	v_lshlrev_b32_e32 v68, 16, v177
	v_and_b32_e32 v69, 0xffff0000, v177
	v_cvt_pk_bf16_f32 v81, v90, v91
	v_pk_add_f32 v[90:91], v[68:69], v[70:71] neg_lo:[0,1] neg_hi:[0,1]
	s_waitcnt vmcnt(22)
	v_lshlrev_b32_e32 v68, 16, v174
	v_and_b32_e32 v69, 0xffff0000, v174
	v_pk_add_f32 v[72:73], v[68:69], v[72:73] neg_lo:[0,1] neg_hi:[0,1]
	v_lshlrev_b32_e32 v68, 16, v175
	v_and_b32_e32 v69, 0xffff0000, v175
	v_pk_add_f32 v[74:75], v[68:69], v[74:75] neg_lo:[0,1] neg_hi:[0,1]
	s_waitcnt vmcnt(21)
	v_lshlrev_b32_e32 v68, 16, v172
	v_and_b32_e32 v69, 0xffff0000, v172
	v_and_b32_e32 v85, 0xffff0000, v191
	v_pk_add_f32 v[76:77], v[68:69], v[76:77] neg_lo:[0,1] neg_hi:[0,1]
	v_lshlrev_b32_e32 v68, 16, v173
	v_and_b32_e32 v69, 0xffff0000, v173
	v_sub_f32_e32 v95, v85, v95
	v_cvt_pk_bf16_f32 v85, v82, v83
	v_cvt_pk_bf16_f32 v86, v196, v197
	v_cvt_pk_bf16_f32 v87, v194, v195
	global_load_dwordx2 v[196:197], v[188:189], off offset:-64
	global_load_dwordx2 v[194:195], v[188:189], off offset:-48
	global_load_dwordx2 v[192:193], v[188:189], off offset:-32
	global_load_dwordx2 v[190:191], v[188:189], off offset:-16
	global_load_dwordx2 v[186:187], v[188:189], off
	global_load_dwordx2 v[176:177], v[188:189], off offset:16
	global_load_dwordx2 v[174:175], v[188:189], off offset:32
	global_load_dwordx2 v[172:173], v[188:189], off offset:48
	v_sub_f32_e32 v79, v69, v79
	v_sub_f32_e32 v78, v68, v78
	v_cvt_pk_bf16_f32 v68, v64, v65
	v_cvt_pk_bf16_f32 v69, v66, v67
	v_cvt_pk_bf16_f32 v70, v88, v89
	v_cvt_pk_bf16_f32 v71, v90, v91
	v_cvt_pk_bf16_f32 v82, v92, v93
	v_cvt_pk_bf16_f32 v83, v94, v95
	global_store_dwordx4 v[210:211], v[84:87], off
	global_store_dwordx4 v[210:211], v[80:83], off offset:1024
	v_cvt_pk_bf16_f32 v64, v72, v73
	v_cvt_pk_bf16_f32 v65, v74, v75
	v_cvt_pk_bf16_f32 v66, v76, v77
	v_cvt_pk_bf16_f32 v67, v78, v79
	global_store_dwordx4 v[210:211], v[68:71], off offset:2048
	global_store_dwordx4 v[210:211], v[64:67], off offset:3072
	v_add_u32_e32 v211, 0x4000, v207
	ds_read2_b64 v[72:75], v211 offset0:64 offset1:66
	ds_read2_b64 v[76:79], v211 offset0:68 offset1:70
	ds_read2_b64 v[88:91], v211 offset0:72 offset1:74
	ds_read2_b64 v[92:95], v211 offset0:76 offset1:78
	v_pk_mul_f32 v[14:15], v[14:15], v[170:171] op_sel_hi:[1,0]
	v_pk_mul_f32 v[12:13], v[12:13], v[170:171] op_sel_hi:[1,0]
	v_pk_mul_f32 v[10:11], v[10:11], v[170:171] op_sel_hi:[1,0]
	v_pk_mul_f32 v[8:9], v[8:9], v[170:171] op_sel_hi:[1,0]
	v_pk_mul_f32 v[6:7], v[6:7], v[170:171] op_sel_hi:[1,0]
	v_pk_mul_f32 v[4:5], v[4:5], v[170:171] op_sel_hi:[1,0]
	v_pk_mul_f32 v[2:3], v[2:3], v[170:171] op_sel_hi:[1,0]
	v_pk_mul_f32 v[0:1], v[0:1], v[170:171] op_sel_hi:[1,0]
	v_add_u32_e32 v210, 0x5000, v207
	s_waitcnt lgkmcnt(3)
	v_mfma_f32_32x32x16_bf16 v[0:15], v[72:75], v[84:87], v[0:15]
	s_waitcnt lgkmcnt(2)
	v_mfma_f32_32x32x16_bf16 v[0:15], v[76:79], v[80:83], v[0:15]
	s_waitcnt lgkmcnt(1)
	v_mfma_f32_32x32x16_bf16 v[0:15], v[88:91], v[68:71], v[0:15]
	ds_read2_b64 v[72:75], v210 offset0:96 offset1:98
	ds_read2_b64 v[76:79], v210 offset0:100 offset1:102
	ds_read2_b64 v[88:91], v210 offset0:104 offset1:106
	ds_read2_b64 v[212:215], v210 offset0:108 offset1:110
	s_waitcnt lgkmcnt(4)
	v_mfma_f32_32x32x16_bf16 v[0:15], v[92:95], v[64:67], v[0:15]
	v_mul_f32_e64 v30, v30, v170
	v_mul_f32_e64 v31, v31, v170
	v_mul_f32_e64 v28, v28, v170
	v_mul_f32_e64 v29, v29, v170
	v_mul_f32_e64 v26, v26, v170
	v_mul_f32_e64 v27, v27, v170
	v_pk_mul_f32 v[24:25], v[24:25], v[170:171] op_sel_hi:[1,0]
	v_pk_mul_f32 v[22:23], v[22:23], v[170:171] op_sel_hi:[1,0]
	v_pk_mul_f32 v[20:21], v[20:21], v[170:171] op_sel_hi:[1,0]
	v_pk_mul_f32 v[18:19], v[18:19], v[170:171] op_sel_hi:[1,0]
	v_pk_mul_f32 v[16:17], v[16:17], v[170:171] op_sel_hi:[1,0]
	v_add_u32_e32 v209, 0x6000, v207
	s_waitcnt lgkmcnt(3)
	v_mfma_f32_32x32x16_bf16 v[16:31], v[72:75], v[84:87], v[16:31]
	s_waitcnt lgkmcnt(2)
	v_mfma_f32_32x32x16_bf16 v[16:31], v[76:79], v[80:83], v[16:31]
	s_waitcnt lgkmcnt(1)
	v_mfma_f32_32x32x16_bf16 v[16:31], v[88:91], v[68:71], v[16:31]
	ds_read2_b64 v[72:75], v209 offset0:128 offset1:130
	ds_read2_b64 v[76:79], v209 offset0:132 offset1:134
	ds_read2_b64 v[88:91], v209 offset0:136 offset1:138
	ds_read2_b64 v[92:95], v209 offset0:140 offset1:142
	s_waitcnt lgkmcnt(4)
	v_mfma_f32_32x32x16_bf16 v[16:31], v[212:215], v[64:67], v[16:31]
	v_mul_f32_e64 v46, v46, v170
	v_mul_f32_e64 v47, v47, v170
	v_mul_f32_e64 v44, v44, v170
	v_mul_f32_e64 v45, v45, v170
	v_mul_f32_e64 v42, v42, v170
	v_mul_f32_e64 v43, v43, v170
	v_pk_mul_f32 v[40:41], v[40:41], v[170:171] op_sel_hi:[1,0]
	v_pk_mul_f32 v[38:39], v[38:39], v[170:171] op_sel_hi:[1,0]
	v_pk_mul_f32 v[36:37], v[36:37], v[170:171] op_sel_hi:[1,0]
	v_pk_mul_f32 v[34:35], v[34:35], v[170:171] op_sel_hi:[1,0]
	v_pk_mul_f32 v[32:33], v[32:33], v[170:171] op_sel_hi:[1,0]
	v_add_u32_e32 v185, 0x7000, v207
	s_waitcnt lgkmcnt(3)
	v_mfma_f32_32x32x16_bf16 v[32:47], v[72:75], v[84:87], v[32:47]
	s_waitcnt lgkmcnt(2)
	v_mfma_f32_32x32x16_bf16 v[32:47], v[76:79], v[80:83], v[32:47]
	s_waitcnt lgkmcnt(1)
	v_mfma_f32_32x32x16_bf16 v[32:47], v[88:91], v[68:71], v[32:47]
	ds_read2_b64 v[72:75], v185 offset0:160 offset1:162
	ds_read2_b64 v[76:79], v185 offset0:164 offset1:166
	ds_read2_b64 v[88:91], v185 offset0:168 offset1:170
	ds_read2_b64 v[214:217], v185 offset0:172 offset1:174
	s_waitcnt lgkmcnt(4)
	v_mfma_f32_32x32x16_bf16 v[32:47], v[92:95], v[64:67], v[32:47]
	v_mul_f32_e64 v62, v170, v62
	v_mul_f32_e64 v63, v170, v63
	v_mul_f32_e64 v60, v170, v60
	v_mul_f32_e64 v61, v170, v61
	v_mul_f32_e64 v58, v170, v58
	v_mul_f32_e64 v59, v170, v59
	v_pk_mul_f32 v[56:57], v[170:171], v[56:57] op_sel_hi:[0,1]
	v_pk_mul_f32 v[54:55], v[170:171], v[54:55] op_sel_hi:[0,1]
	v_pk_mul_f32 v[52:53], v[170:171], v[52:53] op_sel_hi:[0,1]
	v_pk_mul_f32 v[50:51], v[170:171], v[50:51] op_sel_hi:[0,1]
	v_pk_mul_f32 v[48:49], v[170:171], v[48:49] op_sel_hi:[0,1]
	v_cndmask_b32_e64 v212, 0, 1, s[12:13]
	s_waitcnt lgkmcnt(0)
	v_mfma_f32_32x32x16_bf16 v[48:63], v[72:75], v[84:87], v[48:63]
	s_barrier
	s_waitcnt vmcnt(36)
	ds_write2_b64 v171, v[128:129], v[130:131] offset1:1
	s_waitcnt vmcnt(35)
	ds_write2_b64 v199, v[132:133], v[134:135] offset1:1
	s_waitcnt vmcnt(34)
	ds_write2_b64 v200, v[136:137], v[138:139] offset1:1
	s_waitcnt vmcnt(33)
	ds_write2_b64 v201, v[140:141], v[142:143] offset1:1
	s_waitcnt vmcnt(32)
	ds_write2_b64 v202, v[144:145], v[146:147] offset1:1
	s_waitcnt vmcnt(31)
	ds_write2_b64 v203, v[148:149], v[150:151] offset1:1
	s_waitcnt vmcnt(30)
	ds_write2_b64 v204, v[152:153], v[154:155] offset1:1
	s_waitcnt vmcnt(29)
	ds_write2_b64 v205, v[156:157], v[158:159] offset1:1
	s_waitcnt lgkmcnt(0)
	s_barrier
	v_mfma_f32_32x32x16_bf16 v[48:63], v[76:79], v[80:83], v[48:63]
	s_cmpk_gt_u32 s16, 0x7c
	v_mfma_f32_32x32x16_bf16 v[48:63], v[88:91], v[68:71], v[48:63]
	v_lshlrev_b32_e32 v68, 2, v212
	global_load_dword v170, v68, s[6:7]
	v_mfma_f32_32x32x16_bf16 v[48:63], v[214:217], v[64:67], v[48:63]
	s_add_i32 s4, s0, s16
	s_add_i32 s4, s4, 3
	s_ashr_i32 s5, s4, 31
	s_lshl_b64 s[4:5], s[4:5], 14
	s_add_u32 s18, s2, s4
	s_addc_u32 s19, s3, s5
	s_add_u32 s4, s14, s4
	s_addc_u32 s5, s15, s5
	v_lshl_add_u64 v[64:65], s[18:19], 0, v[160:161]
	v_lshl_add_u64 v[66:67], s[4:5], 0, v[160:161]
	global_load_dwordx4 v[128:131], v[64:65], off
	global_load_dwordx4 v[132:135], v[66:67], off
	v_lshl_add_u64 v[64:65], s[18:19], 0, v[162:163]
	v_lshl_add_u64 v[66:67], s[4:5], 0, v[162:163]
	global_load_dwordx4 v[136:139], v[64:65], off
	global_load_dwordx4 v[140:143], v[66:67], off
	v_lshl_add_u64 v[64:65], s[18:19], 0, v[164:165]
	v_lshl_add_u64 v[66:67], s[4:5], 0, v[164:165]
	global_load_dwordx4 v[144:147], v[64:65], off
	global_load_dwordx4 v[148:151], v[66:67], off
	v_lshl_add_u64 v[64:65], s[18:19], 0, v[166:167]
	v_lshl_add_u64 v[66:67], s[4:5], 0, v[166:167]
	global_load_dwordx4 v[152:155], v[64:65], off
	global_load_dwordx4 v[156:159], v[66:67], off
.LBB0_1205:
	ds_read2_b64 v[64:67], v206 offset1:2
	ds_read2_b64 v[214:217], v206 offset0:4 offset1:6
	ds_read2_b64 v[68:71], v208 offset0:32 offset1:34
	ds_read2_b64 v[218:221], v208 offset0:36 offset1:38
	v_add_u32_e32 v238, 4, v184
	v_ashrrev_i32_e32 v239, 31, v238
	v_lshlrev_b64 v[230:231], 13, v[238:239]
	v_cvt_pk_bf16_f32 v222, v0, v1
	v_cvt_pk_bf16_f32 v223, v2, v3
	v_cvt_pk_bf16_f32 v224, v4, v5
	v_cvt_pk_bf16_f32 v225, v6, v7
	v_cvt_pk_bf16_f32 v226, v8, v9
	v_cvt_pk_bf16_f32 v227, v10, v11
	s_waitcnt lgkmcnt(3)
	v_mfma_f32_32x32x16_bf16 v[80:95], v[64:67], v[222:225], 0
	v_cvt_pk_bf16_f32 v228, v12, v13
	v_cvt_pk_bf16_f32 v229, v14, v15
	v_lshl_add_u64 v[240:241], v[178:179], 0, v[230:231]
	global_store_dwordx4 v[240:241], v[222:225], off
	global_store_dwordx4 v[240:241], v[226:229], off offset:1024
	s_waitcnt lgkmcnt(1)
	v_mfma_f32_32x32x16_bf16 v[64:79], v[68:71], v[222:225], 0
	v_mfma_f32_32x32x16_bf16 v[80:95], v[214:217], v[226:229], v[80:95]
	ds_read2_b64 v[214:217], v206 offset0:8 offset1:10
	ds_read2_b64 v[222:225], v206 offset0:12 offset1:14
	ds_read2_b64 v[230:233], v208 offset0:40 offset1:42
	ds_read2_b64 v[234:237], v208 offset0:44 offset1:46
	s_waitcnt lgkmcnt(4)
	v_mfma_f32_32x32x16_bf16 v[64:79], v[218:221], v[226:229], v[64:79]
	v_cvt_pk_bf16_f32 v218, v16, v17
	v_cvt_pk_bf16_f32 v219, v18, v19
	v_cvt_pk_bf16_f32 v220, v20, v21
	v_cvt_pk_bf16_f32 v221, v22, v23
	s_waitcnt lgkmcnt(3)
	s_nop 0
	v_mfma_f32_32x32x16_bf16 v[80:95], v[214:217], v[218:221], v[80:95]
	v_cvt_pk_bf16_f32 v214, v24, v25
	v_cvt_pk_bf16_f32 v215, v26, v27
	v_cvt_pk_bf16_f32 v216, v28, v29
	v_cvt_pk_bf16_f32 v217, v30, v31
	global_store_dwordx4 v[240:241], v[218:221], off offset:2048
	global_store_dwordx4 v[240:241], v[214:217], off offset:3072
	s_waitcnt lgkmcnt(1)
	v_mfma_f32_32x32x16_bf16 v[64:79], v[230:233], v[218:221], v[64:79]
	v_mfma_f32_32x32x16_bf16 v[80:95], v[222:225], v[214:217], v[80:95]
	ds_read2_b64 v[218:221], v206 offset0:16 offset1:18
	ds_read2_b64 v[222:225], v206 offset0:20 offset1:22
	ds_read2_b64 v[226:229], v208 offset0:48 offset1:50
	ds_read2_b64 v[230:233], v208 offset0:52 offset1:54
	s_waitcnt lgkmcnt(4)
	v_mfma_f32_32x32x16_bf16 v[64:79], v[234:237], v[214:217], v[64:79]
	v_cvt_pk_bf16_f32 v214, v32, v33
	v_cvt_pk_bf16_f32 v215, v34, v35
	v_cvt_pk_bf16_f32 v216, v36, v37
	v_cvt_pk_bf16_f32 v217, v38, v39
	v_add_co_u32_e32 v240, vcc, s1, v240
	s_waitcnt lgkmcnt(3)
	v_mfma_f32_32x32x16_bf16 v[80:95], v[218:221], v[214:217], v[80:95]
	v_cvt_pk_bf16_f32 v218, v40, v41
	v_cvt_pk_bf16_f32 v219, v42, v43
	v_cvt_pk_bf16_f32 v220, v44, v45
	v_cvt_pk_bf16_f32 v221, v46, v47
	v_addc_co_u32_e32 v241, vcc, 0, v241, vcc
	global_store_dwordx4 v[240:241], v[214:217], off
	global_store_dwordx4 v[240:241], v[218:221], off offset:1024
	s_waitcnt lgkmcnt(1)
	v_mfma_f32_32x32x16_bf16 v[64:79], v[226:229], v[214:217], v[64:79]
	v_mfma_f32_32x32x16_bf16 v[80:95], v[222:225], v[218:221], v[80:95]
	ds_read2_b64 v[214:217], v206 offset0:24 offset1:26
	ds_read2_b64 v[222:225], v206 offset0:28 offset1:30
	ds_read2_b64 v[226:229], v208 offset0:56 offset1:58
	ds_read2_b64 v[234:237], v208 offset0:60 offset1:62
	s_waitcnt lgkmcnt(4)
	v_mfma_f32_32x32x16_bf16 v[64:79], v[230:233], v[218:221], v[64:79]
	v_cvt_pk_bf16_f32 v218, v48, v49
	v_cvt_pk_bf16_f32 v219, v50, v51
	v_cvt_pk_bf16_f32 v220, v52, v53
	v_cvt_pk_bf16_f32 v221, v54, v55
	v_cvt_pk_bf16_f32 v230, v56, v57
	v_cvt_pk_bf16_f32 v231, v58, v59
	s_waitcnt lgkmcnt(3)
	v_mfma_f32_32x32x16_bf16 v[80:95], v[214:217], v[218:221], v[80:95]
	v_cvt_pk_bf16_f32 v232, v60, v61
	v_cvt_pk_bf16_f32 v233, v62, v63
	s_waitcnt vmcnt(26)
	v_lshlrev_b32_e32 v216, 16, v196
	v_and_b32_e32 v217, 0xffff0000, v196
	v_lshlrev_b64 v[214:215], 12, v[238:239]
	v_lshlrev_b32_e32 v238, 16, v197
	v_and_b32_e32 v239, 0xffff0000, v197
	s_waitcnt lgkmcnt(1)
	v_mfma_f32_32x32x16_bf16 v[64:79], v[226:229], v[218:221], v[64:79]
	s_waitcnt vmcnt(23)
	v_lshlrev_b32_e32 v208, 16, v191
	v_and_b32_e32 v213, 0xffff0000, v191
	v_lshl_add_u64 v[214:215], v[180:181], 0, v[214:215]
	v_cmp_ne_u32_e64 s[4:5], 1, v212
	s_andn2_b64 vcc, exec, s[12:13]
	global_store_dwordx4 v[240:241], v[218:221], off offset:2048
	global_store_dwordx4 v[240:241], v[230:233], off offset:3072
	v_mfma_f32_32x32x16_bf16 v[80:95], v[222:225], v[230:233], v[80:95]
	s_waitcnt lgkmcnt(0)
	v_mfma_f32_32x32x16_bf16 v[64:79], v[234:237], v[230:233], v[64:79]
	s_nop 9
	v_add_f32_e64 v80, v216, -v80
	v_add_f32_e64 v81, v217, -v81
	v_lshlrev_b32_e32 v216, 16, v194
	v_and_b32_e32 v217, 0xffff0000, v194
	v_add_f32_e64 v84, v216, -v84
	v_add_f32_e64 v85, v217, -v85
	v_lshlrev_b32_e32 v216, 16, v195
	v_and_b32_e32 v217, 0xffff0000, v195
	v_pk_add_f32 v[86:87], v[216:217], v[86:87] neg_lo:[0,1] neg_hi:[0,1]
	v_lshlrev_b32_e32 v216, 16, v192
	v_and_b32_e32 v217, 0xffff0000, v192
	v_pk_add_f32 v[82:83], v[238:239], v[82:83] neg_lo:[0,1] neg_hi:[0,1]
	v_pk_add_f32 v[88:89], v[216:217], v[88:89] neg_lo:[0,1] neg_hi:[0,1]
	v_cvt_pk_bf16_f32 v80, v80, v81
	v_cvt_pk_bf16_f32 v81, v82, v83
	v_cvt_pk_bf16_f32 v82, v84, v85
	v_cvt_pk_bf16_f32 v84, v88, v89
	s_waitcnt vmcnt(24)
	v_lshlrev_b32_e32 v88, 16, v186
	v_and_b32_e32 v89, 0xffff0000, v186
	v_pk_add_f32 v[64:65], v[88:89], v[64:65] neg_lo:[0,1] neg_hi:[0,1]
	v_lshlrev_b32_e32 v88, 16, v187
	v_and_b32_e32 v89, 0xffff0000, v187
	v_pk_add_f32 v[66:67], v[88:89], v[66:67] neg_lo:[0,1] neg_hi:[0,1]
	s_waitcnt vmcnt(23)
	v_lshlrev_b32_e32 v88, 16, v176
	v_and_b32_e32 v89, 0xffff0000, v176
	v_pk_add_f32 v[68:69], v[88:89], v[68:69] neg_lo:[0,1] neg_hi:[0,1]
	v_lshlrev_b32_e32 v88, 16, v177
	v_and_b32_e32 v89, 0xffff0000, v177
	v_pk_add_f32 v[70:71], v[88:89], v[70:71] neg_lo:[0,1] neg_hi:[0,1]
	s_waitcnt vmcnt(22)
	v_lshlrev_b32_e32 v88, 16, v174
	v_and_b32_e32 v89, 0xffff0000, v174
	v_pk_add_f32 v[72:73], v[88:89], v[72:73] neg_lo:[0,1] neg_hi:[0,1]
	v_lshlrev_b32_e32 v88, 16, v175
	v_and_b32_e32 v89, 0xffff0000, v175
	v_lshlrev_b32_e32 v216, 16, v193
	v_and_b32_e32 v217, 0xffff0000, v193
	v_pk_add_f32 v[74:75], v[88:89], v[74:75] neg_lo:[0,1] neg_hi:[0,1]
	s_waitcnt vmcnt(21)
	v_lshlrev_b32_e32 v88, 16, v172
	v_and_b32_e32 v89, 0xffff0000, v172
	v_pk_add_f32 v[90:91], v[216:217], v[90:91] neg_lo:[0,1] neg_hi:[0,1]
	v_lshlrev_b32_e32 v216, 16, v190
	v_and_b32_e32 v217, 0xffff0000, v190
	v_pk_add_f32 v[76:77], v[88:89], v[76:77] neg_lo:[0,1] neg_hi:[0,1]
	v_lshlrev_b32_e32 v88, 16, v173
	v_and_b32_e32 v89, 0xffff0000, v173
	s_add_i32 s98, s0, s16
	s_add_i32 s98, s98, 2
	s_ashr_i32 s99, s98, 31
	s_lshl_b64 s[98:99], s[98:99], 14
	v_lshl_add_u64 v[246:247], v[182:183], 0, s[98:99]
	global_load_dwordx2 v[196:197], v[246:247], off
	global_load_dwordx2 v[194:195], v[246:247], off offset:16
	global_load_dwordx2 v[192:193], v[246:247], off offset:32
	global_load_dwordx2 v[190:191], v[246:247], off offset:48
	global_load_dwordx2 v[186:187], v[246:247], off offset:64
	global_load_dwordx2 v[176:177], v[246:247], off offset:80
	global_load_dwordx2 v[174:175], v[246:247], off offset:96
	global_load_dwordx2 v[172:173], v[246:247], off offset:112
	v_pk_add_f32 v[92:93], v[216:217], v[92:93] neg_lo:[0,1] neg_hi:[0,1]
	v_sub_f32_e32 v95, v213, v95
	v_sub_f32_e32 v94, v208, v94
	v_sub_f32_e32 v79, v89, v79
	v_sub_f32_e32 v78, v88, v78
	v_cvt_pk_bf16_f32 v83, v86, v87
	v_cvt_pk_bf16_f32 v85, v90, v91
	v_cvt_pk_bf16_f32 v86, v92, v93
	v_cvt_pk_bf16_f32 v87, v94, v95
	v_cvt_pk_bf16_f32 v64, v64, v65
	v_cvt_pk_bf16_f32 v65, v66, v67
	v_cvt_pk_bf16_f32 v66, v68, v69
	v_cvt_pk_bf16_f32 v67, v70, v71
	v_cvt_pk_bf16_f32 v68, v72, v73
	v_cvt_pk_bf16_f32 v69, v74, v75
	v_cvt_pk_bf16_f32 v70, v76, v77
	v_cvt_pk_bf16_f32 v71, v78, v79
	global_store_dwordx4 v[214:215], v[80:83], off
	global_store_dwordx4 v[214:215], v[84:87], off offset:1024
	global_store_dwordx4 v[214:215], v[64:67], off offset:2048
	global_store_dwordx4 v[214:215], v[68:71], off offset:3072

	.amdhsa_kernel _Z4mega6Params
		.amdhsa_group_segment_fixed_size 73744
		.amdhsa_private_segment_fixed_size 0
		.amdhsa_kernarg_size 496
		.amdhsa_user_sgpr_count 2
		.amdhsa_user_sgpr_dispatch_ptr 0
		.amdhsa_user_sgpr_queue_ptr 0
		.amdhsa_user_sgpr_kernarg_segment_ptr 1
		.amdhsa_user_sgpr_dispatch_id 0
		.amdhsa_user_sgpr_kernarg_preload_length 0
		.amdhsa_user_sgpr_kernarg_preload_offset 0
		.amdhsa_user_sgpr_private_segment_size 0
		.amdhsa_uses_dynamic_stack 0
		.amdhsa_enable_private_segment 0
		.amdhsa_system_sgpr_workgroup_id_x 1
		.amdhsa_system_sgpr_workgroup_id_y 0
		.amdhsa_system_sgpr_workgroup_id_z 0
		.amdhsa_system_sgpr_workgroup_info 0
		.amdhsa_system_vgpr_workitem_id 2
		.amdhsa_next_free_vgpr 256
		.amdhsa_next_free_sgpr 100
		.amdhsa_accum_offset 256
		.amdhsa_reserve_vcc 1
		.amdhsa_float_round_mode_32 0
		.amdhsa_float_round_mode_16_64 0
		.amdhsa_float_denorm_mode_32 3
		.amdhsa_float_denorm_mode_16_64 3
		.amdhsa_dx10_clamp 1
		.amdhsa_ieee_mode 1
		.amdhsa_fp16_overflow 0
		.amdhsa_tg_split 0
		.amdhsa_exception_fp_ieee_invalid_op 0
		.amdhsa_exception_fp_denorm_src 0
		.amdhsa_exception_fp_ieee_div_zero 0
		.amdhsa_exception_fp_ieee_overflow 0
		.amdhsa_exception_fp_ieee_underflow 0
		.amdhsa_exception_fp_ieee_inexact 0
		.amdhsa_exception_int_div_zero 0
	.end_amdhsa_kernel

amdhsa.kernels:
  - .agpr_count:     0
    .args:
      - .offset:         0
        .size:           240
        .value_kind:     by_value
      - .offset:         240
        .size:           4
        .value_kind:     hidden_block_count_x
      - .offset:         244
        .size:           4
        .value_kind:     hidden_block_count_y
      - .offset:         248
        .size:           4
        .value_kind:     hidden_block_count_z
      - .offset:         252
        .size:           2
        .value_kind:     hidden_group_size_x
      - .offset:         254
        .size:           2
        .value_kind:     hidden_group_size_y
      - .offset:         256
        .size:           2
        .value_kind:     hidden_group_size_z
      - .offset:         258
        .size:           2
        .value_kind:     hidden_remainder_x
      - .offset:         260
        .size:           2
        .value_kind:     hidden_remainder_y
      - .offset:         262
        .size:           2
        .value_kind:     hidden_remainder_z
      - .offset:         280
        .size:           8
        .value_kind:     hidden_global_offset_x
      - .offset:         288
        .size:           8
        .value_kind:     hidden_global_offset_y
      - .offset:         296
        .size:           8
        .value_kind:     hidden_global_offset_z
      - .offset:         304
        .size:           2
        .value_kind:     hidden_grid_dims
      - .offset:         328
        .size:           8
        .value_kind:     hidden_multigrid_sync_arg
    .group_segment_fixed_size: 73744
    .kernarg_segment_align: 8
    .kernarg_segment_size: 496
    .language:       OpenCL C
    .language_version:
      - 2
      - 0
    .max_flat_workgroup_size: 256
    .name:           _Z4mega6Params
    .private_segment_fixed_size: 0
    .sgpr_count:     106
    .sgpr_spill_count: 91
    .symbol:         _Z4mega6Params.kd
    .uniform_work_group_size: 1
    .uses_dynamic_stack: false
    .vgpr_count:     256
    .vgpr_spill_count: 0
    .wavefront_size: 64
